# prologue adaLN-modulation GEMV: column-group index permuted so the two workgroups reading the two 64-B halves of a w_mod line sit on the same XCD and share it in L2
# speedup vs baseline: 1.0081x; 1.0043x over previous
.LBB0_31:
	s_andn2_b64 vcc, exec, s[20:21]
	s_cbranch_vccnz .LBB0_37
	s_add_i32 s2, s38, 0xfffff740
	s_cmpk_gt_u32 s2, 0xbf
	s_cselect_b64 s[20:21], -1, 0
	s_add_i32 s22, s38, 0xfffff680
	s_cmpk_lt_u32 s2, 0xc0
	s_cselect_b32 s2, s2, s22
	s_and_b32 s22, s2, 7
	s_lshl_b32 s22, s22, 1
	s_bfe_u32 s23, s2, 0x10003
	s_or_b32 s22, s22, s23
	s_andn2_b32 s2, s2, 15
	s_or_b32 s2, s2, s22
	s_lshl_b32 s2, s2, 4
	s_and_b64 s[22:23], s[20:21], exec
	s_cselect_b32 s22, 0xc00000, 0
	v_or_b32_e32 v0, s2, v18
	v_mov_b32_e32 v2, s22
	v_mov_b32_e32 v3, v17
	v_mov_b32_e32 v1, v17
	v_lshl_add_u64 v[0:1], v[0:1], 2, v[2:3]
	v_mov_b32_e32 v4, 0
	v_lshl_add_u64 v[0:1], v[22:23], 0, v[0:1]
	s_mov_b64 s[22:23], 0
	v_mov_b32_e32 v5, v4
	v_mov_b32_e32 v2, v4
	v_mov_b32_e32 v3, v4
